# MLA: O accumulated transposed (A = V fragment, B = P), lane-local rescale and 1/l, permlane32_swap pairs + 8 dwordx4 row stores instead of 64 two-byte stores per lane
# baseline (speedup 1.0000x reference)
.LBB0_546:
	s_branch .Lconv_entry
.LBB0_551:
	s_cmpk_lt_i32 s15, 0x200
	s_cselect_b64 s[10:11], -1, 0
	s_cmpk_gt_i32 s15, 0x1ff
	s_mov_b64 s[8:9], -1
	s_cbranch_scc1 .LBB0_553
	s_ashr_i32 s8, s15, 7
	s_ashr_i32 s9, s8, 31
	s_lshl_b32 s1, s15, 8
	s_lshl_b64 s[4:5], s[8:9], 12
	s_and_b32 s50, s1, 0xf00
	s_or_b32 s4, s4, s50
	s_mul_i32 s1, s5, 0xc00
	s_mul_hi_u32 s6, s4, 0xc00
	s_bfe_u32 s0, s15, 0x30004
	s_add_i32 s6, s6, s1
	s_mul_i32 s1, s4, 0xc00
	v_readlane_b32 s7, v248, 55
	s_add_u32 s1, s7, s1
	v_readlane_b32 s7, v248, 56
	s_addc_u32 s6, s7, s6
	s_mul_i32 s7, s0, 0x180
	s_add_u32 s16, s1, s7
	s_addc_u32 s17, s6, 0
	s_lshl_b64 s[4:5], s[4:5], 12
	s_add_u32 s1, s46, s4
	s_addc_u32 s5, s47, s5
	s_lshl_b32 s4, s0, 8
	s_add_u32 s4, s1, s4
	s_addc_u32 s5, s5, 0
	s_lshl_b32 s1, s8, 8
	s_lshl_b32 s6, s8, 12
	s_add_i32 s13, s1, 0x4000
	s_mov_b64 s[8:9], 0

.Lmla_skipv1_o:
	v_add_f32_e32 v212, v68, v212
	v_exp_f32_e32 v70, v70
	v_add_f32_e32 v212, v69, v212
	v_exp_f32_e32 v71, v71
	s_waitcnt lgkmcnt(3)
	v_mfma_f32_32x32x16_bf16 v[80:95], v[238:241], v[116:119], v[80:95]
	ds_read_b128 v[238:241], v191 offset:57344
	v_add_f32_e32 v212, v70, v212
	v_exp_f32_e32 v72, v72
	v_add_f32_e32 v212, v71, v212
	v_exp_f32_e32 v73, v73
	s_waitcnt lgkmcnt(3)
	v_mfma_f32_32x32x16_bf16 v[80:95], v[242:245], v[112:115], v[80:95]
	ds_read_b128 v[242:245], v192 offset:57344
	s_mov_b32 m0, s23
	v_lshl_add_u64 v[254:255], v[160:161], 1, s[16:17]
	global_load_lds_dwordx4 v[254:255], off
	v_add_f32_e32 v212, v72, v212
	v_exp_f32_e32 v74, v74
	v_add_f32_e32 v212, v73, v212
	v_exp_f32_e32 v75, v75
	s_waitcnt lgkmcnt(3)
	v_mfma_f32_32x32x16_bf16 v[80:95], v[230:233], v[108:111], v[80:95]
	v_add_u32_e32 v211, 0x6000, v203
	ds_read_b128 v[230:233], v211 offset:49152
	v_add_f32_e32 v212, v74, v212
	v_exp_f32_e32 v76, v76
	v_add_f32_e32 v212, v75, v212
	v_exp_f32_e32 v77, v77
	s_waitcnt lgkmcnt(3)
	v_mfma_f32_32x32x16_bf16 v[80:95], v[234:237], v[104:107], v[80:95]
	v_add_u32_e32 v211, 0x6000, v204
	ds_read_b128 v[234:237], v211 offset:49152
	s_mov_b32 m0, s7
	v_lshl_add_u64 v[254:255], v[162:163], 1, s[16:17]
	global_load_lds_dwordx4 v[254:255], off
	v_add_f32_e32 v212, v76, v212
	v_exp_f32_e32 v78, v78
	v_add_f32_e32 v212, v77, v212
	v_exp_f32_e32 v79, v79
	s_waitcnt lgkmcnt(3)
	v_mfma_f32_32x32x16_bf16 v[80:95], v[238:241], v[100:103], v[80:95]
	v_add_u32_e32 v211, 0x6000, v205
	ds_read_b128 v[238:241], v211 offset:49152
	v_add_f32_e32 v212, v78, v212
	v_add_f32_e32 v212, v79, v212
	v_mov_b32_e32 v213, v212
	s_waitcnt lgkmcnt(3)
	v_mfma_f32_32x32x16_bf16 v[80:95], v[242:245], v[96:99], v[80:95]
	v_add_u32_e32 v211, 0x6000, v206
	ds_read_b128 v[242:245], v211 offset:49152
	s_mov_b32 m0, s30
	v_mad_i64_i32 v[254:255], s[0:1], s0, v180, v[168:169]
	global_load_lds_dwordx4 v[254:255], off
	s_add_u32 s100, s16, 0x100
	s_addc_u32 s101, s17, 0
	v_cvt_pk_bf16_f32 v152, v64, v65
	v_cvt_pk_bf16_f32 v153, v66, v67
	v_cvt_pk_bf16_f32 v154, v68, v69
	s_waitcnt lgkmcnt(3)
	v_mfma_f32_32x32x16_bf16 v[80:95], v[230:233], v[128:131], v[80:95]
	v_add_u32_e32 v211, v209, v194
	ds_read_b128 v[230:233], v211 offset:8192
	v_cvt_pk_bf16_f32 v155, v70, v71
	v_cvt_pk_bf16_f32 v156, v72, v73
	v_cvt_pk_bf16_f32 v157, v74, v75
	s_waitcnt lgkmcnt(3)
	v_mfma_f32_32x32x16_bf16 v[80:95], v[234:237], v[132:135], v[80:95]
	v_add_u32_e32 v211, v209, v195
	ds_read_b128 v[234:237], v211 offset:8192
	v_cvt_pk_bf16_f32 v158, v76, v77
	v_cvt_pk_bf16_f32 v159, v78, v79
	v_permlane32_swap_b32_e32 v212, v213
	s_waitcnt lgkmcnt(3)
	v_mfma_f32_32x32x16_bf16 v[80:95], v[238:241], v[136:139], v[80:95]
	v_add_u32_e32 v211, v209, v196
	ds_read_b128 v[238:241], v211 offset:8192
	v_add_f32_e32 v252, v212, v213
	v_fma_f32 v183, v207, v183, v252
	v_permlane32_swap_b32_e32 v152, v154
	s_waitcnt lgkmcnt(3)
	v_mfma_f32_32x32x16_bf16 v[80:95], v[242:245], v[140:143], v[80:95]
	v_add_u32_e32 v211, v209, v197
	ds_read_b128 v[242:245], v211 offset:8192
	v_permlane32_swap_b32_e32 v153, v155
	v_permlane32_swap_b32_e32 v156, v158
	v_permlane32_swap_b32_e32 v157, v159
	s_waitcnt lgkmcnt(3)
	v_mfma_f32_32x32x16_bf16 v[64:79], v[230:233], v[124:127], 0
	v_add_u32_e32 v211, v209, v198
	ds_read_b128 v[230:233], v211 offset:8192
	s_waitcnt lgkmcnt(3)
	v_mfma_f32_32x32x16_bf16 v[64:79], v[234:237], v[120:123], v[64:79]
	v_add_u32_e32 v211, v209, v199
	ds_read_b128 v[234:237], v211 offset:8192
	s_waitcnt lgkmcnt(3)
	v_mfma_f32_32x32x16_bf16 v[64:79], v[238:241], v[116:119], v[64:79]
	v_add_u32_e32 v211, v209, v200
	ds_read_b128 v[238:241], v211 offset:8192
	s_waitcnt lgkmcnt(3)
	v_mfma_f32_32x32x16_bf16 v[64:79], v[242:245], v[112:115], v[64:79]
	v_add_u32_e32 v211, v209, v201
	ds_read_b128 v[242:245], v211 offset:8192
	s_waitcnt lgkmcnt(3)
	v_mfma_f32_32x32x16_bf16 v[64:79], v[230:233], v[108:111], v[64:79]
	v_add_u32_e32 v211, 0x6000, v203
	ds_read_b128 v[230:233], v211 offset:53248
	s_waitcnt lgkmcnt(3)
	v_mfma_f32_32x32x16_bf16 v[64:79], v[234:237], v[104:107], v[64:79]
	v_add_u32_e32 v211, 0x6000, v204
	ds_read_b128 v[234:237], v211 offset:53248
	s_waitcnt lgkmcnt(3)
	v_mfma_f32_32x32x16_bf16 v[64:79], v[238:241], v[100:103], v[64:79]
	v_add_u32_e32 v211, 0x6000, v205
	ds_read_b128 v[238:241], v211 offset:53248
	v_max_f32_e32 v249, v80, v81
	v_max3_f32 v249, v249, v82, v83
	s_waitcnt lgkmcnt(3)
	v_mfma_f32_32x32x16_bf16 v[64:79], v[242:245], v[96:99], v[64:79]
	v_add_u32_e32 v211, 0x6000, v206
	ds_read_b128 v[242:245], v211 offset:53248
	v_max3_f32 v249, v249, v84, v85
	v_max3_f32 v249, v249, v86, v87
	s_waitcnt lgkmcnt(3)
	v_mfma_f32_32x32x16_bf16 v[64:79], v[230:233], v[128:131], v[64:79]
	ds_read_b64_tr_b16 v[214:215], v185
	ds_read_b64_tr_b16 v[216:217], v185 offset:2048
	v_max3_f32 v249, v249, v88, v89
	v_max3_f32 v249, v249, v90, v91
	s_waitcnt lgkmcnt(4)
	v_mfma_f32_32x32x16_bf16 v[64:79], v[234:237], v[132:135], v[64:79]
	ds_read_b64_tr_b16 v[218:219], v185 offset:4096
	ds_read_b64_tr_b16 v[220:221], v185 offset:6144
	v_max3_f32 v249, v249, v92, v93
	v_max3_f32 v249, v249, v94, v95
	s_waitcnt lgkmcnt(5)
	v_mfma_f32_32x32x16_bf16 v[64:79], v[238:241], v[136:139], v[64:79]
	ds_read_b64_tr_b16 v[222:223], v185 offset:8192
	ds_read_b64_tr_b16 v[224:225], v185 offset:10240
	s_waitcnt lgkmcnt(6)
	v_mfma_f32_32x32x16_bf16 v[64:79], v[242:245], v[140:143], v[64:79]
	ds_read_b64_tr_b16 v[226:227], v185 offset:12288
	ds_read_b64_tr_b16 v[228:229], v185 offset:14336
	s_waitcnt lgkmcnt(6)
	v_mfma_f32_32x32x16_bf16 v[0:15], v[214:217], v[144:147], v[0:15]
	ds_read_b64_tr_b16 v[214:215], v185 offset:512
	ds_read_b64_tr_b16 v[216:217], v185 offset:2560
	s_waitcnt lgkmcnt(6)
	v_mfma_f32_32x32x16_bf16 v[0:15], v[218:221], v[148:151], v[0:15]
	ds_read_b64_tr_b16 v[218:219], v185 offset:4608
	ds_read_b64_tr_b16 v[220:221], v185 offset:6656
	s_waitcnt lgkmcnt(6)
	v_mfma_f32_32x32x16_bf16 v[0:15], v[222:225], v[152:155], v[0:15]
	ds_read_b64_tr_b16 v[222:223], v185 offset:8704
	ds_read_b64_tr_b16 v[224:225], v185 offset:10752
	s_waitcnt lgkmcnt(6)
	v_mfma_f32_32x32x16_bf16 v[0:15], v[226:229], v[156:159], v[0:15]
	ds_read_b64_tr_b16 v[226:227], v185 offset:12800
	ds_read_b64_tr_b16 v[228:229], v185 offset:14848
	s_waitcnt lgkmcnt(6)
	v_mfma_f32_32x32x16_bf16 v[48:63], v[214:217], v[144:147], v[48:63]
	ds_read_b64_tr_b16 v[214:215], v185 offset:1024
	ds_read_b64_tr_b16 v[216:217], v185 offset:3072
	v_max3_f32 v249, v249, v64, v65
	v_max3_f32 v249, v249, v66, v67
	v_max3_f32 v249, v249, v68, v69
	v_max3_f32 v249, v249, v70, v71
	v_max3_f32 v249, v249, v72, v73
	v_max3_f32 v249, v249, v74, v75
	v_max3_f32 v249, v249, v76, v77
	v_max3_f32 v249, v249, v78, v79
	s_waitcnt lgkmcnt(6)
	v_mfma_f32_32x32x16_bf16 v[48:63], v[218:221], v[148:151], v[48:63]
	ds_read_b64_tr_b16 v[218:219], v185 offset:5120
	ds_read_b64_tr_b16 v[220:221], v185 offset:7168
	v_mov_b32_e32 v250, v249
	s_nop 1
	v_permlane32_swap_b32_e32 v249, v250
	v_max_f32_e32 v249, v249, v250
	v_sub_f32_e32 v250, v249, v208
	v_cmp_ge_f32_e32 vcc, s40, v250
	v_max_f32_e32 v249, v208, v249
	v_sub_f32_e32 v250, v208, v249
	s_waitcnt lgkmcnt(6)
	v_mfma_f32_32x32x16_bf16 v[48:63], v[222:225], v[152:155], v[48:63]
	ds_read_b64_tr_b16 v[222:223], v185 offset:9216
	ds_read_b64_tr_b16 v[224:225], v185 offset:11264
	v_mul_f32_e32 v250, 0x3dd53b94, v250
	v_exp_f32_e32 v250, v250
	s_cmp_eq_u64 vcc, exec
	s_cselect_b64 s[10:11], -1, 0
	v_cndmask_b32_e64 v207, v250, 1.0, s[10:11]
	v_cndmask_b32_e64 v208, v249, v208, s[10:11]
	v_mul_f32_e32 v251, 0xbdd53b94, v208
	v_fmamk_f32 v80, v80, 0x3dd53b94, v251
	s_waitcnt lgkmcnt(6)
	v_mfma_f32_32x32x16_bf16 v[48:63], v[226:229], v[156:159], v[48:63]
	ds_read_b64_tr_b16 v[226:227], v185 offset:13312
	ds_read_b64_tr_b16 v[228:229], v185 offset:15360
	v_fmamk_f32 v81, v81, 0x3dd53b94, v251
	v_fmamk_f32 v82, v82, 0x3dd53b94, v251
	v_fmamk_f32 v83, v83, 0x3dd53b94, v251
	v_fmamk_f32 v84, v84, 0x3dd53b94, v251
	v_fmamk_f32 v85, v85, 0x3dd53b94, v251
	v_fmamk_f32 v86, v86, 0x3dd53b94, v251
	v_fmamk_f32 v87, v87, 0x3dd53b94, v251
	s_waitcnt lgkmcnt(6)
	v_mfma_f32_32x32x16_bf16 v[32:47], v[214:217], v[144:147], v[32:47]
	ds_read_b64_tr_b16 v[214:215], v185 offset:1536
	ds_read_b64_tr_b16 v[216:217], v185 offset:3584
	v_fmamk_f32 v88, v88, 0x3dd53b94, v251
	v_fmamk_f32 v89, v89, 0x3dd53b94, v251
	v_fmamk_f32 v90, v90, 0x3dd53b94, v251
	v_fmamk_f32 v91, v91, 0x3dd53b94, v251
	v_fmamk_f32 v92, v92, 0x3dd53b94, v251
	v_fmamk_f32 v93, v93, 0x3dd53b94, v251
	v_fmamk_f32 v94, v94, 0x3dd53b94, v251
	s_waitcnt lgkmcnt(6)
	v_mfma_f32_32x32x16_bf16 v[32:47], v[218:221], v[148:151], v[32:47]
	ds_read_b64_tr_b16 v[218:219], v185 offset:5632
	ds_read_b64_tr_b16 v[220:221], v185 offset:7680
	v_fmamk_f32 v95, v95, 0x3dd53b94, v251
	v_exp_f32_e32 v80, v80
	v_fmamk_f32 v64, v64, 0x3dd53b94, v251
	v_exp_f32_e32 v81, v81
	v_fmamk_f32 v65, v65, 0x3dd53b94, v251
	v_add_f32_e32 v212, 0, v80
	v_exp_f32_e32 v82, v82
	s_waitcnt lgkmcnt(6)
	v_mfma_f32_32x32x16_bf16 v[32:47], v[222:225], v[152:155], v[32:47]
	ds_read_b64_tr_b16 v[222:223], v185 offset:9728
	ds_read_b64_tr_b16 v[224:225], v185 offset:11776
	v_fmamk_f32 v66, v66, 0x3dd53b94, v251
	v_add_f32_e32 v212, v81, v212
	v_exp_f32_e32 v83, v83
	v_fmamk_f32 v67, v67, 0x3dd53b94, v251
	v_add_f32_e32 v212, v82, v212
	v_exp_f32_e32 v84, v84
	v_fmamk_f32 v68, v68, 0x3dd53b94, v251
	s_waitcnt lgkmcnt(6)
	v_mfma_f32_32x32x16_bf16 v[32:47], v[226:229], v[156:159], v[32:47]
	ds_read_b64_tr_b16 v[226:227], v185 offset:13824
	ds_read_b64_tr_b16 v[228:229], v185 offset:15872
	v_add_f32_e32 v212, v83, v212
	v_exp_f32_e32 v85, v85
	v_fmamk_f32 v69, v69, 0x3dd53b94, v251
	v_add_f32_e32 v212, v84, v212
	v_exp_f32_e32 v86, v86
	v_fmamk_f32 v70, v70, 0x3dd53b94, v251
	v_add_f32_e32 v212, v85, v212
	s_waitcnt lgkmcnt(6)
	v_mfma_f32_32x32x16_bf16 v[16:31], v[214:217], v[144:147], v[16:31]
	v_exp_f32_e32 v87, v87
	v_fmamk_f32 v71, v71, 0x3dd53b94, v251
	v_add_f32_e32 v212, v86, v212
	v_exp_f32_e32 v88, v88
	v_fmamk_f32 v72, v72, 0x3dd53b94, v251
	v_add_f32_e32 v212, v87, v212
	v_exp_f32_e32 v89, v89
	s_waitcnt lgkmcnt(4)
	v_mfma_f32_32x32x16_bf16 v[16:31], v[218:221], v[148:151], v[16:31]
	v_fmamk_f32 v73, v73, 0x3dd53b94, v251
	v_add_f32_e32 v212, v88, v212
	v_exp_f32_e32 v90, v90
	v_fmamk_f32 v74, v74, 0x3dd53b94, v251
	v_add_f32_e32 v212, v89, v212
	v_exp_f32_e32 v91, v91
	v_fmamk_f32 v75, v75, 0x3dd53b94, v251
	s_waitcnt lgkmcnt(2)
	v_mfma_f32_32x32x16_bf16 v[16:31], v[222:225], v[152:155], v[16:31]
	v_add_f32_e32 v212, v90, v212
	v_exp_f32_e32 v92, v92
	v_fmamk_f32 v76, v76, 0x3dd53b94, v251
	v_add_f32_e32 v212, v91, v212
	v_exp_f32_e32 v93, v93
	v_fmamk_f32 v77, v77, 0x3dd53b94, v251
	v_add_f32_e32 v212, v92, v212
	s_waitcnt lgkmcnt(0)
	v_mfma_f32_32x32x16_bf16 v[16:31], v[226:229], v[156:159], v[16:31]
	v_exp_f32_e32 v94, v94
	v_fmamk_f32 v78, v78, 0x3dd53b94, v251
	v_add_f32_e32 v212, v93, v212
	v_exp_f32_e32 v95, v95
	v_fmamk_f32 v79, v79, 0x3dd53b94, v251
	v_add_f32_e32 v212, v94, v212
	v_add_f32_e32 v212, v95, v212
	v_cvt_pk_bf16_f32 v144, v80, v81
	v_cvt_pk_bf16_f32 v145, v82, v83
	v_cvt_pk_bf16_f32 v146, v84, v85
	v_cvt_pk_bf16_f32 v147, v86, v87
	v_cvt_pk_bf16_f32 v148, v88, v89
	v_cvt_pk_bf16_f32 v149, v90, v91
	v_cvt_pk_bf16_f32 v150, v92, v93
	v_cvt_pk_bf16_f32 v151, v94, v95
	v_permlane32_swap_b32_e32 v144, v146
	v_permlane32_swap_b32_e32 v145, v147
	v_permlane32_swap_b32_e32 v148, v150
	v_permlane32_swap_b32_e32 v149, v151
	v_cmp_gt_f32_e32 vcc, 1.0, v207
	s_cbranch_vccz .Lmla_noresc_o
	v_mul_f32_e32 v0, v207, v0
	v_mul_f32_e32 v1, v207, v1
	v_mul_f32_e32 v2, v207, v2
	v_mul_f32_e32 v3, v207, v3
	v_mul_f32_e32 v4, v207, v4
	v_mul_f32_e32 v5, v207, v5
	v_mul_f32_e32 v6, v207, v6
	v_mul_f32_e32 v7, v207, v7
	v_mul_f32_e32 v8, v207, v8
	v_mul_f32_e32 v9, v207, v9
	v_mul_f32_e32 v10, v207, v10
	v_mul_f32_e32 v11, v207, v11
	v_mul_f32_e32 v12, v207, v12
	v_mul_f32_e32 v13, v207, v13
	v_mul_f32_e32 v14, v207, v14
	v_mul_f32_e32 v15, v207, v15
	v_mul_f32_e32 v48, v207, v48
	v_mul_f32_e32 v49, v207, v49
	v_mul_f32_e32 v50, v207, v50
	v_mul_f32_e32 v51, v207, v51
	v_mul_f32_e32 v52, v207, v52
	v_mul_f32_e32 v53, v207, v53
	v_mul_f32_e32 v54, v207, v54
	v_mul_f32_e32 v55, v207, v55
	v_mul_f32_e32 v56, v207, v56
	v_mul_f32_e32 v57, v207, v57
	v_mul_f32_e32 v58, v207, v58
	v_mul_f32_e32 v59, v207, v59
	v_mul_f32_e32 v60, v207, v60
	v_mul_f32_e32 v61, v207, v61
	v_mul_f32_e32 v62, v207, v62
	v_mul_f32_e32 v63, v207, v63
	v_mul_f32_e32 v32, v207, v32
	v_mul_f32_e32 v33, v207, v33
	v_mul_f32_e32 v34, v207, v34
	v_mul_f32_e32 v35, v207, v35
	v_mul_f32_e32 v36, v207, v36
	v_mul_f32_e32 v37, v207, v37
	v_mul_f32_e32 v38, v207, v38
	v_mul_f32_e32 v39, v207, v39
	v_mul_f32_e32 v40, v207, v40
	v_mul_f32_e32 v41, v207, v41
	v_mul_f32_e32 v42, v207, v42
	v_mul_f32_e32 v43, v207, v43
	v_mul_f32_e32 v44, v207, v44
	v_mul_f32_e32 v45, v207, v45
	v_mul_f32_e32 v46, v207, v46
	v_mul_f32_e32 v47, v207, v47
	v_mul_f32_e32 v16, v207, v16
	v_mul_f32_e32 v17, v207, v17
	v_mul_f32_e32 v18, v207, v18
	v_mul_f32_e32 v19, v207, v19
	v_mul_f32_e32 v20, v207, v20
	v_mul_f32_e32 v21, v207, v21
	v_mul_f32_e32 v22, v207, v22
	v_mul_f32_e32 v23, v207, v23
	v_mul_f32_e32 v24, v207, v24
	v_mul_f32_e32 v25, v207, v25
	v_mul_f32_e32 v26, v207, v26
	v_mul_f32_e32 v27, v207, v27
	v_mul_f32_e32 v28, v207, v28
	v_mul_f32_e32 v29, v207, v29
	v_mul_f32_e32 v30, v207, v30
	v_mul_f32_e32 v31, v207, v31
.Lmla_noresc_o:
	s_add_i32 s58, s58, 1
	s_waitcnt vmcnt(0) lgkmcnt(0)
	s_barrier
	ds_read_b128 v[230:233], v193 offset:32768
	ds_read_b128 v[234:237], v186 offset:32768
	ds_read_b128 v[238:241], v187 offset:32768
	ds_read_b128 v[242:245], v188 offset:32768
	s_cmp_lt_u32 s58, s18
	s_cselect_b32 s0, 0, s18
	s_cselect_b32 s1, s6, s13
	s_lshl_b32 s0, s0, 6
	s_sub_i32 s0, s1, s0
	s_add_i32 s0, s51, s0
	s_add_i32 s0, s0, 64
	s_ashr_i32 s1, s0, 31
	s_lshl_b64 s[10:11], s[0:1], 12
	s_add_u32 s16, s20, s10
	s_addc_u32 s17, s21, s11
	v_exp_f32_e32 v64, v64
	v_exp_f32_e32 v65, v65
	v_add_f32_e32 v212, v64, v212
	v_exp_f32_e32 v66, v66
	v_add_f32_e32 v212, v65, v212
	v_exp_f32_e32 v67, v67
	s_waitcnt lgkmcnt(3)
	v_mfma_f32_32x32x16_bf16 v[80:95], v[230:233], v[124:127], 0
	ds_read_b128 v[230:233], v189 offset:32768
	s_mov_b32 m0, s22
	v_lshl_add_u64 v[254:255], v[164:165], 1, s[100:101]
	global_load_lds_dwordx4 v[254:255], off
	v_add_f32_e32 v212, v66, v212
	v_exp_f32_e32 v68, v68
	v_add_f32_e32 v212, v67, v212
	v_exp_f32_e32 v69, v69
	s_waitcnt lgkmcnt(3)
	v_mfma_f32_32x32x16_bf16 v[80:95], v[234:237], v[120:123], v[80:95]
	ds_read_b128 v[234:237], v190 offset:32768
	s_mov_b32 m0, s31
	v_lshl_add_u64 v[254:255], v[166:167], 1, s[100:101]
	global_load_lds_dwordx4 v[254:255], off
	v_add_f32_e32 v212, v68, v212
	v_exp_f32_e32 v70, v70
	v_add_f32_e32 v212, v69, v212
	v_exp_f32_e32 v71, v71
	s_waitcnt lgkmcnt(3)
	v_mfma_f32_32x32x16_bf16 v[80:95], v[238:241], v[116:119], v[80:95]
	ds_read_b128 v[238:241], v191 offset:32768
	v_add_f32_e32 v212, v70, v212
	v_exp_f32_e32 v72, v72
	v_add_f32_e32 v212, v71, v212
	v_exp_f32_e32 v73, v73
	s_waitcnt lgkmcnt(3)
	v_mfma_f32_32x32x16_bf16 v[80:95], v[242:245], v[112:115], v[80:95]
	ds_read_b128 v[242:245], v192 offset:32768
	s_mov_b32 m0, s44
	v_lshl_add_u64 v[254:255], v[160:161], 1, s[16:17]
	global_load_lds_dwordx4 v[254:255], off
	v_add_f32_e32 v212, v72, v212
	v_exp_f32_e32 v74, v74
	v_add_f32_e32 v212, v73, v212
	v_exp_f32_e32 v75, v75
	s_waitcnt lgkmcnt(3)
	v_mfma_f32_32x32x16_bf16 v[80:95], v[230:233], v[108:111], v[80:95]
	ds_read_b128 v[230:233], v203 offset:49152
	v_add_f32_e32 v212, v74, v212
	v_exp_f32_e32 v76, v76
	v_add_f32_e32 v212, v75, v212
	v_exp_f32_e32 v77, v77
	s_waitcnt lgkmcnt(3)
	v_mfma_f32_32x32x16_bf16 v[80:95], v[234:237], v[104:107], v[80:95]
	ds_read_b128 v[234:237], v204 offset:49152
	s_mov_b32 m0, s45
	v_lshl_add_u64 v[254:255], v[162:163], 1, s[16:17]
	global_load_lds_dwordx4 v[254:255], off
	v_add_f32_e32 v212, v76, v212
	v_exp_f32_e32 v78, v78
	v_add_f32_e32 v212, v77, v212
	v_exp_f32_e32 v79, v79
	s_waitcnt lgkmcnt(3)
	v_mfma_f32_32x32x16_bf16 v[80:95], v[238:241], v[100:103], v[80:95]
	ds_read_b128 v[238:241], v205 offset:49152
	v_add_f32_e32 v212, v78, v212
	v_add_f32_e32 v212, v79, v212
	v_mov_b32_e32 v213, v212
	s_waitcnt lgkmcnt(3)
	v_mfma_f32_32x32x16_bf16 v[80:95], v[242:245], v[96:99], v[80:95]
	ds_read_b128 v[242:245], v206 offset:49152
	s_mov_b32 m0, s49
	v_mad_i64_i32 v[254:255], s[0:1], s0, v180, v[168:169]
	global_load_lds_dwordx4 v[254:255], off
	s_add_u32 s100, s16, 0x100
	s_addc_u32 s101, s17, 0
	v_cvt_pk_bf16_f32 v152, v64, v65
	v_cvt_pk_bf16_f32 v153, v66, v67
	v_cvt_pk_bf16_f32 v154, v68, v69
	s_waitcnt lgkmcnt(3)
	v_mfma_f32_32x32x16_bf16 v[80:95], v[230:233], v[128:131], v[80:95]
	ds_read_b128 v[230:233], v193 offset:40960
	v_cvt_pk_bf16_f32 v155, v70, v71
	v_cvt_pk_bf16_f32 v156, v72, v73
	v_cvt_pk_bf16_f32 v157, v74, v75
	s_waitcnt lgkmcnt(3)
	v_mfma_f32_32x32x16_bf16 v[80:95], v[234:237], v[132:135], v[80:95]
	ds_read_b128 v[234:237], v186 offset:40960
	v_cvt_pk_bf16_f32 v158, v76, v77
	v_cvt_pk_bf16_f32 v159, v78, v79
	v_permlane32_swap_b32_e32 v212, v213
	s_waitcnt lgkmcnt(3)
	v_mfma_f32_32x32x16_bf16 v[80:95], v[238:241], v[136:139], v[80:95]
	ds_read_b128 v[238:241], v187 offset:40960
	v_add_f32_e32 v252, v212, v213
	v_fma_f32 v183, v207, v183, v252
	v_permlane32_swap_b32_e32 v152, v154
	s_waitcnt lgkmcnt(3)
	v_mfma_f32_32x32x16_bf16 v[80:95], v[242:245], v[140:143], v[80:95]
	ds_read_b128 v[242:245], v188 offset:40960
	v_permlane32_swap_b32_e32 v153, v155
	v_permlane32_swap_b32_e32 v156, v158
	v_permlane32_swap_b32_e32 v157, v159
	s_waitcnt lgkmcnt(3)
	v_mfma_f32_32x32x16_bf16 v[64:79], v[230:233], v[124:127], 0
	ds_read_b128 v[230:233], v189 offset:40960
	s_waitcnt lgkmcnt(3)
	v_mfma_f32_32x32x16_bf16 v[64:79], v[234:237], v[120:123], v[64:79]
	ds_read_b128 v[234:237], v190 offset:40960
	s_waitcnt lgkmcnt(3)
	v_mfma_f32_32x32x16_bf16 v[64:79], v[238:241], v[116:119], v[64:79]
	ds_read_b128 v[238:241], v191 offset:40960
	s_waitcnt lgkmcnt(3)
	v_mfma_f32_32x32x16_bf16 v[64:79], v[242:245], v[112:115], v[64:79]
	ds_read_b128 v[242:245], v192 offset:40960
	s_waitcnt lgkmcnt(3)
	v_mfma_f32_32x32x16_bf16 v[64:79], v[230:233], v[108:111], v[64:79]
	ds_read_b128 v[230:233], v203 offset:53248
	s_waitcnt lgkmcnt(3)
	v_mfma_f32_32x32x16_bf16 v[64:79], v[234:237], v[104:107], v[64:79]
	ds_read_b128 v[234:237], v204 offset:53248
	s_waitcnt lgkmcnt(3)
	v_mfma_f32_32x32x16_bf16 v[64:79], v[238:241], v[100:103], v[64:79]
	ds_read_b128 v[238:241], v205 offset:53248
	v_max_f32_e32 v249, v80, v81
	v_max3_f32 v249, v249, v82, v83
	s_waitcnt lgkmcnt(3)
	v_mfma_f32_32x32x16_bf16 v[64:79], v[242:245], v[96:99], v[64:79]
	ds_read_b128 v[242:245], v206 offset:53248
	v_max3_f32 v249, v249, v84, v85
	v_max3_f32 v249, v249, v86, v87
	s_waitcnt lgkmcnt(3)
	v_mfma_f32_32x32x16_bf16 v[64:79], v[230:233], v[128:131], v[64:79]
	ds_read_b64_tr_b16 v[214:215], v184
	ds_read_b64_tr_b16 v[216:217], v184 offset:2048
	v_max3_f32 v249, v249, v88, v89
	v_max3_f32 v249, v249, v90, v91
	s_waitcnt lgkmcnt(4)
	v_mfma_f32_32x32x16_bf16 v[64:79], v[234:237], v[132:135], v[64:79]
	ds_read_b64_tr_b16 v[218:219], v184 offset:4096
	ds_read_b64_tr_b16 v[220:221], v184 offset:6144
	v_max3_f32 v249, v249, v92, v93
	v_max3_f32 v249, v249, v94, v95
	s_waitcnt lgkmcnt(5)
	v_mfma_f32_32x32x16_bf16 v[64:79], v[238:241], v[136:139], v[64:79]
	ds_read_b64_tr_b16 v[222:223], v184 offset:8192
	ds_read_b64_tr_b16 v[224:225], v184 offset:10240
	s_waitcnt lgkmcnt(6)
	v_mfma_f32_32x32x16_bf16 v[64:79], v[242:245], v[140:143], v[64:79]
	ds_read_b64_tr_b16 v[226:227], v184 offset:12288
	ds_read_b64_tr_b16 v[228:229], v184 offset:14336
	s_waitcnt lgkmcnt(6)
	v_mfma_f32_32x32x16_bf16 v[0:15], v[214:217], v[144:147], v[0:15]
	ds_read_b64_tr_b16 v[214:215], v184 offset:512
	ds_read_b64_tr_b16 v[216:217], v184 offset:2560
	s_waitcnt lgkmcnt(6)
	v_mfma_f32_32x32x16_bf16 v[0:15], v[218:221], v[148:151], v[0:15]
	ds_read_b64_tr_b16 v[218:219], v184 offset:4608
	ds_read_b64_tr_b16 v[220:221], v184 offset:6656
	s_waitcnt lgkmcnt(6)
	v_mfma_f32_32x32x16_bf16 v[0:15], v[222:225], v[152:155], v[0:15]
	ds_read_b64_tr_b16 v[222:223], v184 offset:8704
	ds_read_b64_tr_b16 v[224:225], v184 offset:10752
	s_waitcnt lgkmcnt(6)
	v_mfma_f32_32x32x16_bf16 v[0:15], v[226:229], v[156:159], v[0:15]
	ds_read_b64_tr_b16 v[226:227], v184 offset:12800
	ds_read_b64_tr_b16 v[228:229], v184 offset:14848
	s_waitcnt lgkmcnt(6)
	v_mfma_f32_32x32x16_bf16 v[48:63], v[214:217], v[144:147], v[48:63]
	ds_read_b64_tr_b16 v[214:215], v184 offset:1024
	ds_read_b64_tr_b16 v[216:217], v184 offset:3072
	v_max3_f32 v249, v249, v64, v65
	v_max3_f32 v249, v249, v66, v67
	v_max3_f32 v249, v249, v68, v69
	v_max3_f32 v249, v249, v70, v71
	v_max3_f32 v249, v249, v72, v73
	v_max3_f32 v249, v249, v74, v75
	v_max3_f32 v249, v249, v76, v77
	v_max3_f32 v249, v249, v78, v79
	s_waitcnt lgkmcnt(6)
	v_mfma_f32_32x32x16_bf16 v[48:63], v[218:221], v[148:151], v[48:63]
	ds_read_b64_tr_b16 v[218:219], v184 offset:5120
	ds_read_b64_tr_b16 v[220:221], v184 offset:7168
	v_mov_b32_e32 v250, v249
	s_nop 1
	v_permlane32_swap_b32_e32 v249, v250
	v_max_f32_e32 v249, v249, v250
	v_sub_f32_e32 v250, v249, v208
	v_cmp_ge_f32_e32 vcc, s40, v250
	v_max_f32_e32 v249, v208, v249
	v_sub_f32_e32 v250, v208, v249
	s_waitcnt lgkmcnt(6)
	v_mfma_f32_32x32x16_bf16 v[48:63], v[222:225], v[152:155], v[48:63]
	ds_read_b64_tr_b16 v[222:223], v184 offset:9216
	ds_read_b64_tr_b16 v[224:225], v184 offset:11264
	v_mul_f32_e32 v250, 0x3dd53b94, v250
	v_exp_f32_e32 v250, v250
	s_cmp_eq_u64 vcc, exec
	s_cselect_b64 s[10:11], -1, 0
	v_cndmask_b32_e64 v207, v250, 1.0, s[10:11]
	v_cndmask_b32_e64 v208, v249, v208, s[10:11]
	v_mul_f32_e32 v251, 0xbdd53b94, v208
	v_fmamk_f32 v80, v80, 0x3dd53b94, v251
	s_waitcnt lgkmcnt(6)
	v_mfma_f32_32x32x16_bf16 v[48:63], v[226:229], v[156:159], v[48:63]
	ds_read_b64_tr_b16 v[226:227], v184 offset:13312
	ds_read_b64_tr_b16 v[228:229], v184 offset:15360
	v_fmamk_f32 v81, v81, 0x3dd53b94, v251
	v_fmamk_f32 v82, v82, 0x3dd53b94, v251
	v_fmamk_f32 v83, v83, 0x3dd53b94, v251
	v_fmamk_f32 v84, v84, 0x3dd53b94, v251
	v_fmamk_f32 v85, v85, 0x3dd53b94, v251
	v_fmamk_f32 v86, v86, 0x3dd53b94, v251
	v_fmamk_f32 v87, v87, 0x3dd53b94, v251
	s_waitcnt lgkmcnt(6)
	v_mfma_f32_32x32x16_bf16 v[32:47], v[214:217], v[144:147], v[32:47]
	ds_read_b64_tr_b16 v[214:215], v184 offset:1536
	ds_read_b64_tr_b16 v[216:217], v184 offset:3584
	v_fmamk_f32 v88, v88, 0x3dd53b94, v251
	v_fmamk_f32 v89, v89, 0x3dd53b94, v251
	v_fmamk_f32 v90, v90, 0x3dd53b94, v251
	v_fmamk_f32 v91, v91, 0x3dd53b94, v251
	v_fmamk_f32 v92, v92, 0x3dd53b94, v251
	v_fmamk_f32 v93, v93, 0x3dd53b94, v251
	v_fmamk_f32 v94, v94, 0x3dd53b94, v251
	s_waitcnt lgkmcnt(6)
	v_mfma_f32_32x32x16_bf16 v[32:47], v[218:221], v[148:151], v[32:47]
	ds_read_b64_tr_b16 v[218:219], v184 offset:5632
	ds_read_b64_tr_b16 v[220:221], v184 offset:7680
	v_fmamk_f32 v95, v95, 0x3dd53b94, v251
	v_exp_f32_e32 v80, v80
	v_fmamk_f32 v64, v64, 0x3dd53b94, v251
	v_exp_f32_e32 v81, v81
	v_fmamk_f32 v65, v65, 0x3dd53b94, v251
	v_add_f32_e32 v212, 0, v80
	v_exp_f32_e32 v82, v82
	s_waitcnt lgkmcnt(6)
	v_mfma_f32_32x32x16_bf16 v[32:47], v[222:225], v[152:155], v[32:47]
	ds_read_b64_tr_b16 v[222:223], v184 offset:9728
	ds_read_b64_tr_b16 v[224:225], v184 offset:11776
	v_fmamk_f32 v66, v66, 0x3dd53b94, v251
	v_add_f32_e32 v212, v81, v212
	v_exp_f32_e32 v83, v83
	v_fmamk_f32 v67, v67, 0x3dd53b94, v251
	v_add_f32_e32 v212, v82, v212
	v_exp_f32_e32 v84, v84
	v_fmamk_f32 v68, v68, 0x3dd53b94, v251
	s_waitcnt lgkmcnt(6)
	v_mfma_f32_32x32x16_bf16 v[32:47], v[226:229], v[156:159], v[32:47]
	ds_read_b64_tr_b16 v[226:227], v184 offset:13824
	ds_read_b64_tr_b16 v[228:229], v184 offset:15872
	v_add_f32_e32 v212, v83, v212
	v_exp_f32_e32 v85, v85
	v_fmamk_f32 v69, v69, 0x3dd53b94, v251
	v_add_f32_e32 v212, v84, v212
	v_exp_f32_e32 v86, v86
	v_fmamk_f32 v70, v70, 0x3dd53b94, v251
	v_add_f32_e32 v212, v85, v212
	s_waitcnt lgkmcnt(6)
	v_mfma_f32_32x32x16_bf16 v[16:31], v[214:217], v[144:147], v[16:31]
	v_exp_f32_e32 v87, v87
	v_fmamk_f32 v71, v71, 0x3dd53b94, v251
	v_add_f32_e32 v212, v86, v212
	v_exp_f32_e32 v88, v88
	v_fmamk_f32 v72, v72, 0x3dd53b94, v251
	v_add_f32_e32 v212, v87, v212
	v_exp_f32_e32 v89, v89
	s_waitcnt lgkmcnt(4)
	v_mfma_f32_32x32x16_bf16 v[16:31], v[218:221], v[148:151], v[16:31]
	v_fmamk_f32 v73, v73, 0x3dd53b94, v251
	v_add_f32_e32 v212, v88, v212
	v_exp_f32_e32 v90, v90
	v_fmamk_f32 v74, v74, 0x3dd53b94, v251
	v_add_f32_e32 v212, v89, v212
	v_exp_f32_e32 v91, v91
	v_fmamk_f32 v75, v75, 0x3dd53b94, v251
	s_waitcnt lgkmcnt(2)
	v_mfma_f32_32x32x16_bf16 v[16:31], v[222:225], v[152:155], v[16:31]
	v_add_f32_e32 v212, v90, v212
	v_exp_f32_e32 v92, v92
	v_fmamk_f32 v76, v76, 0x3dd53b94, v251
	v_add_f32_e32 v212, v91, v212
	v_exp_f32_e32 v93, v93
	v_fmamk_f32 v77, v77, 0x3dd53b94, v251
	v_add_f32_e32 v212, v92, v212
	s_waitcnt lgkmcnt(0)
	v_mfma_f32_32x32x16_bf16 v[16:31], v[226:229], v[156:159], v[16:31]
	v_exp_f32_e32 v94, v94
	v_fmamk_f32 v78, v78, 0x3dd53b94, v251
	v_add_f32_e32 v212, v93, v212
	v_exp_f32_e32 v95, v95
	v_fmamk_f32 v79, v79, 0x3dd53b94, v251
	v_add_f32_e32 v212, v94, v212
	v_add_f32_e32 v212, v95, v212
	v_cvt_pk_bf16_f32 v144, v80, v81
	v_cvt_pk_bf16_f32 v145, v82, v83
	v_cvt_pk_bf16_f32 v146, v84, v85
	v_cvt_pk_bf16_f32 v147, v86, v87
	v_cvt_pk_bf16_f32 v148, v88, v89
	v_cvt_pk_bf16_f32 v149, v90, v91
	v_cvt_pk_bf16_f32 v150, v92, v93
	v_cvt_pk_bf16_f32 v151, v94, v95
	v_permlane32_swap_b32_e32 v144, v146
	v_permlane32_swap_b32_e32 v145, v147
	v_permlane32_swap_b32_e32 v148, v150
	v_permlane32_swap_b32_e32 v149, v151
	v_cmp_gt_f32_e32 vcc, 1.0, v207
	s_cbranch_vccz .Lmla_noresc_e
	v_mul_f32_e32 v0, v207, v0
	v_mul_f32_e32 v1, v207, v1
	v_mul_f32_e32 v2, v207, v2
	v_mul_f32_e32 v3, v207, v3
	v_mul_f32_e32 v4, v207, v4
	v_mul_f32_e32 v5, v207, v5
	v_mul_f32_e32 v6, v207, v6
	v_mul_f32_e32 v7, v207, v7
	v_mul_f32_e32 v8, v207, v8
	v_mul_f32_e32 v9, v207, v9
	v_mul_f32_e32 v10, v207, v10
	v_mul_f32_e32 v11, v207, v11
	v_mul_f32_e32 v12, v207, v12
	v_mul_f32_e32 v13, v207, v13
	v_mul_f32_e32 v14, v207, v14
	v_mul_f32_e32 v15, v207, v15
	v_mul_f32_e32 v48, v207, v48
	v_mul_f32_e32 v49, v207, v49
	v_mul_f32_e32 v50, v207, v50
	v_mul_f32_e32 v51, v207, v51
	v_mul_f32_e32 v52, v207, v52
	v_mul_f32_e32 v53, v207, v53
	v_mul_f32_e32 v54, v207, v54
	v_mul_f32_e32 v55, v207, v55
	v_mul_f32_e32 v56, v207, v56
	v_mul_f32_e32 v57, v207, v57
	v_mul_f32_e32 v58, v207, v58
	v_mul_f32_e32 v59, v207, v59
	v_mul_f32_e32 v60, v207, v60
	v_mul_f32_e32 v61, v207, v61
	v_mul_f32_e32 v62, v207, v62
	v_mul_f32_e32 v63, v207, v63
	v_mul_f32_e32 v32, v207, v32
	v_mul_f32_e32 v33, v207, v33
	v_mul_f32_e32 v34, v207, v34
	v_mul_f32_e32 v35, v207, v35
	v_mul_f32_e32 v36, v207, v36
	v_mul_f32_e32 v37, v207, v37
	v_mul_f32_e32 v38, v207, v38
	v_mul_f32_e32 v39, v207, v39
	v_mul_f32_e32 v40, v207, v40
	v_mul_f32_e32 v41, v207, v41
	v_mul_f32_e32 v42, v207, v42
	v_mul_f32_e32 v43, v207, v43
	v_mul_f32_e32 v44, v207, v44
	v_mul_f32_e32 v45, v207, v45
	v_mul_f32_e32 v46, v207, v46
	v_mul_f32_e32 v47, v207, v47
	v_mul_f32_e32 v16, v207, v16
	v_mul_f32_e32 v17, v207, v17
	v_mul_f32_e32 v18, v207, v18
	v_mul_f32_e32 v19, v207, v19
	v_mul_f32_e32 v20, v207, v20
	v_mul_f32_e32 v21, v207, v21
	v_mul_f32_e32 v22, v207, v22
	v_mul_f32_e32 v23, v207, v23
	v_mul_f32_e32 v24, v207, v24
	v_mul_f32_e32 v25, v207, v25
	v_mul_f32_e32 v26, v207, v26
	v_mul_f32_e32 v27, v207, v27
	v_mul_f32_e32 v28, v207, v28
	v_mul_f32_e32 v29, v207, v29
	v_mul_f32_e32 v30, v207, v30
	v_mul_f32_e32 v31, v207, v31
.Lmla_noresc_e:
	s_add_i32 s58, s58, 1
	s_addk_i32 s51, 0x80
	s_waitcnt vmcnt(0) lgkmcnt(0)
	s_barrier
	s_cmp_ge_u32 s58, s19
	s_cbranch_scc0 .Lmla_loop
	ds_read_b128 v[230:233], v193 offset:57344
	ds_read_b128 v[234:237], v186 offset:57344
	ds_read_b128 v[238:241], v187 offset:57344
	ds_read_b128 v[242:245], v188 offset:57344
	v_exp_f32_e32 v64, v64
	v_exp_f32_e32 v65, v65
	v_add_f32_e32 v212, v64, v212
	v_exp_f32_e32 v66, v66
	v_add_f32_e32 v212, v65, v212
	v_exp_f32_e32 v67, v67
	s_waitcnt lgkmcnt(3)
	v_mfma_f32_32x32x16_bf16 v[80:95], v[230:233], v[124:127], 0
	ds_read_b128 v[230:233], v189 offset:57344
	s_mov_b32 m0, s54
	v_lshl_add_u64 v[254:255], v[164:165], 1, s[100:101]
	global_load_lds_dwordx4 v[254:255], off
	v_add_f32_e32 v212, v66, v212
	v_exp_f32_e32 v68, v68
	v_add_f32_e32 v212, v67, v212
	v_exp_f32_e32 v69, v69
	s_waitcnt lgkmcnt(3)
	v_mfma_f32_32x32x16_bf16 v[80:95], v[234:237], v[120:123], v[80:95]
	ds_read_b128 v[234:237], v190 offset:57344
	s_mov_b32 m0, s55
	v_lshl_add_u64 v[254:255], v[166:167], 1, s[100:101]
	global_load_lds_dwordx4 v[254:255], off
	v_add_f32_e32 v212, v68, v212
	v_exp_f32_e32 v70, v70
	v_add_f32_e32 v212, v69, v212
	v_exp_f32_e32 v71, v71
	s_waitcnt lgkmcnt(3)
	v_mfma_f32_32x32x16_bf16 v[80:95], v[238:241], v[116:119], v[80:95]
	ds_read_b128 v[238:241], v191 offset:57344
	v_add_f32_e32 v212, v70, v212
	v_exp_f32_e32 v72, v72
	v_add_f32_e32 v212, v71, v212
	v_exp_f32_e32 v73, v73
	s_waitcnt lgkmcnt(3)
	v_mfma_f32_32x32x16_bf16 v[80:95], v[242:245], v[112:115], v[80:95]
	ds_read_b128 v[242:245], v192 offset:57344
	v_add_f32_e32 v212, v72, v212
	v_exp_f32_e32 v74, v74
	v_add_f32_e32 v212, v73, v212
	v_exp_f32_e32 v75, v75
	s_waitcnt lgkmcnt(3)
	v_mfma_f32_32x32x16_bf16 v[80:95], v[230:233], v[108:111], v[80:95]
	v_add_u32_e32 v211, 0x6000, v203
	ds_read_b128 v[230:233], v211 offset:49152
	v_add_f32_e32 v212, v74, v212
	v_exp_f32_e32 v76, v76
	v_add_f32_e32 v212, v75, v212
	v_exp_f32_e32 v77, v77
	s_waitcnt lgkmcnt(3)
	v_mfma_f32_32x32x16_bf16 v[80:95], v[234:237], v[104:107], v[80:95]
	v_add_u32_e32 v211, 0x6000, v204
	ds_read_b128 v[234:237], v211 offset:49152
	v_add_f32_e32 v212, v76, v212
	v_exp_f32_e32 v78, v78
	v_add_f32_e32 v212, v77, v212
	v_exp_f32_e32 v79, v79
	s_waitcnt lgkmcnt(3)
	v_mfma_f32_32x32x16_bf16 v[80:95], v[238:241], v[100:103], v[80:95]
	v_add_u32_e32 v211, 0x6000, v205
	ds_read_b128 v[238:241], v211 offset:49152
	v_add_f32_e32 v212, v78, v212
	v_add_f32_e32 v212, v79, v212
	v_mov_b32_e32 v213, v212
	s_waitcnt lgkmcnt(3)
	v_mfma_f32_32x32x16_bf16 v[80:95], v[242:245], v[96:99], v[80:95]
	v_add_u32_e32 v211, 0x6000, v206
	ds_read_b128 v[242:245], v211 offset:49152
	v_cvt_pk_bf16_f32 v152, v64, v65
	v_cvt_pk_bf16_f32 v153, v66, v67
	v_cvt_pk_bf16_f32 v154, v68, v69
	s_waitcnt lgkmcnt(3)
	v_mfma_f32_32x32x16_bf16 v[80:95], v[230:233], v[128:131], v[80:95]
	v_add_u32_e32 v211, v209, v194
	ds_read_b128 v[230:233], v211 offset:8192
	v_cvt_pk_bf16_f32 v155, v70, v71
	v_cvt_pk_bf16_f32 v156, v72, v73
	v_cvt_pk_bf16_f32 v157, v74, v75
	s_waitcnt lgkmcnt(3)
	v_mfma_f32_32x32x16_bf16 v[80:95], v[234:237], v[132:135], v[80:95]
	v_add_u32_e32 v211, v209, v195
	ds_read_b128 v[234:237], v211 offset:8192
	v_cvt_pk_bf16_f32 v158, v76, v77
	v_cvt_pk_bf16_f32 v159, v78, v79
	v_permlane32_swap_b32_e32 v212, v213
	s_waitcnt lgkmcnt(3)
	v_mfma_f32_32x32x16_bf16 v[80:95], v[238:241], v[136:139], v[80:95]
	v_add_u32_e32 v211, v209, v196
	ds_read_b128 v[238:241], v211 offset:8192
	v_add_f32_e32 v252, v212, v213
	v_fma_f32 v183, v207, v183, v252
	v_permlane32_swap_b32_e32 v152, v154
	s_waitcnt lgkmcnt(3)
	v_mfma_f32_32x32x16_bf16 v[80:95], v[242:245], v[140:143], v[80:95]
	v_add_u32_e32 v211, v209, v197
	ds_read_b128 v[242:245], v211 offset:8192
	v_permlane32_swap_b32_e32 v153, v155
	v_permlane32_swap_b32_e32 v156, v158
	v_permlane32_swap_b32_e32 v157, v159
	s_waitcnt lgkmcnt(3)
	v_mfma_f32_32x32x16_bf16 v[64:79], v[230:233], v[124:127], 0
	v_add_u32_e32 v211, v209, v198
	ds_read_b128 v[230:233], v211 offset:8192
	s_waitcnt lgkmcnt(3)
	v_mfma_f32_32x32x16_bf16 v[64:79], v[234:237], v[120:123], v[64:79]
	v_add_u32_e32 v211, v209, v199
	ds_read_b128 v[234:237], v211 offset:8192
	s_waitcnt lgkmcnt(3)
	v_mfma_f32_32x32x16_bf16 v[64:79], v[238:241], v[116:119], v[64:79]
	v_add_u32_e32 v211, v209, v200
	ds_read_b128 v[238:241], v211 offset:8192
	s_waitcnt lgkmcnt(3)
	v_mfma_f32_32x32x16_bf16 v[64:79], v[242:245], v[112:115], v[64:79]
	v_add_u32_e32 v211, v209, v201
	ds_read_b128 v[242:245], v211 offset:8192
	s_waitcnt lgkmcnt(3)
	v_mfma_f32_32x32x16_bf16 v[64:79], v[230:233], v[108:111], v[64:79]
	v_add_u32_e32 v211, 0x6000, v203
	ds_read_b128 v[230:233], v211 offset:53248
	s_waitcnt lgkmcnt(3)
	v_mfma_f32_32x32x16_bf16 v[64:79], v[234:237], v[104:107], v[64:79]
	v_add_u32_e32 v211, 0x6000, v204
	ds_read_b128 v[234:237], v211 offset:53248
	s_waitcnt lgkmcnt(3)
	v_mfma_f32_32x32x16_bf16 v[64:79], v[238:241], v[100:103], v[64:79]
	v_add_u32_e32 v211, 0x6000, v205
	ds_read_b128 v[238:241], v211 offset:53248
	v_max_f32_e32 v249, v80, v81
	v_max3_f32 v249, v249, v82, v83
	s_waitcnt lgkmcnt(3)
	v_mfma_f32_32x32x16_bf16 v[64:79], v[242:245], v[96:99], v[64:79]
	v_add_u32_e32 v211, 0x6000, v206
	ds_read_b128 v[242:245], v211 offset:53248
	v_max3_f32 v249, v249, v84, v85
	v_max3_f32 v249, v249, v86, v87
	s_waitcnt lgkmcnt(3)
	v_mfma_f32_32x32x16_bf16 v[64:79], v[230:233], v[128:131], v[64:79]
	ds_read_b64_tr_b16 v[214:215], v185
	ds_read_b64_tr_b16 v[216:217], v185 offset:2048
	v_max3_f32 v249, v249, v88, v89
	v_max3_f32 v249, v249, v90, v91
	s_waitcnt lgkmcnt(4)
	v_mfma_f32_32x32x16_bf16 v[64:79], v[234:237], v[132:135], v[64:79]
	ds_read_b64_tr_b16 v[218:219], v185 offset:4096
	ds_read_b64_tr_b16 v[220:221], v185 offset:6144
	v_max3_f32 v249, v249, v92, v93
	v_max3_f32 v249, v249, v94, v95
	s_waitcnt lgkmcnt(5)
	v_mfma_f32_32x32x16_bf16 v[64:79], v[238:241], v[136:139], v[64:79]
	ds_read_b64_tr_b16 v[222:223], v185 offset:8192
	ds_read_b64_tr_b16 v[224:225], v185 offset:10240
	s_waitcnt lgkmcnt(6)
	v_mfma_f32_32x32x16_bf16 v[64:79], v[242:245], v[140:143], v[64:79]
	ds_read_b64_tr_b16 v[226:227], v185 offset:12288
	ds_read_b64_tr_b16 v[228:229], v185 offset:14336
	s_waitcnt lgkmcnt(6)
	v_mfma_f32_32x32x16_bf16 v[0:15], v[214:217], v[144:147], v[0:15]
	ds_read_b64_tr_b16 v[214:215], v185 offset:512
	ds_read_b64_tr_b16 v[216:217], v185 offset:2560
	s_waitcnt lgkmcnt(6)
	v_mfma_f32_32x32x16_bf16 v[0:15], v[218:221], v[148:151], v[0:15]
	ds_read_b64_tr_b16 v[218:219], v185 offset:4608
	ds_read_b64_tr_b16 v[220:221], v185 offset:6656
	s_waitcnt lgkmcnt(6)
	v_mfma_f32_32x32x16_bf16 v[0:15], v[222:225], v[152:155], v[0:15]
	ds_read_b64_tr_b16 v[222:223], v185 offset:8704
	ds_read_b64_tr_b16 v[224:225], v185 offset:10752
	s_waitcnt lgkmcnt(6)
	v_mfma_f32_32x32x16_bf16 v[0:15], v[226:229], v[156:159], v[0:15]
	ds_read_b64_tr_b16 v[226:227], v185 offset:12800
	ds_read_b64_tr_b16 v[228:229], v185 offset:14848
	s_waitcnt lgkmcnt(6)
	v_mfma_f32_32x32x16_bf16 v[48:63], v[214:217], v[144:147], v[48:63]
	ds_read_b64_tr_b16 v[214:215], v185 offset:1024
	ds_read_b64_tr_b16 v[216:217], v185 offset:3072
	v_max3_f32 v249, v249, v64, v65
	v_max3_f32 v249, v249, v66, v67
	v_max3_f32 v249, v249, v68, v69
	v_max3_f32 v249, v249, v70, v71
	v_max3_f32 v249, v249, v72, v73
	v_max3_f32 v249, v249, v74, v75
	v_max3_f32 v249, v249, v76, v77
	v_max3_f32 v249, v249, v78, v79
	s_waitcnt lgkmcnt(6)
	v_mfma_f32_32x32x16_bf16 v[48:63], v[218:221], v[148:151], v[48:63]
	ds_read_b64_tr_b16 v[218:219], v185 offset:5120
	ds_read_b64_tr_b16 v[220:221], v185 offset:7168
	v_mov_b32_e32 v250, v249
	s_nop 1
	v_permlane32_swap_b32_e32 v249, v250
	v_max_f32_e32 v249, v249, v250
	v_sub_f32_e32 v250, v249, v208
	v_cmp_ge_f32_e32 vcc, s40, v250
	v_max_f32_e32 v249, v208, v249
	v_sub_f32_e32 v250, v208, v249
	s_waitcnt lgkmcnt(6)
	v_mfma_f32_32x32x16_bf16 v[48:63], v[222:225], v[152:155], v[48:63]
	ds_read_b64_tr_b16 v[222:223], v185 offset:9216
	ds_read_b64_tr_b16 v[224:225], v185 offset:11264
	v_mul_f32_e32 v250, 0x3dd53b94, v250
	v_exp_f32_e32 v250, v250
	s_cmp_eq_u64 vcc, exec
	s_cselect_b64 s[10:11], -1, 0
	v_cndmask_b32_e64 v207, v250, 1.0, s[10:11]
	v_cndmask_b32_e64 v208, v249, v208, s[10:11]
	v_mul_f32_e32 v251, 0xbdd53b94, v208
	v_fmamk_f32 v80, v80, 0x3dd53b94, v251
	s_waitcnt lgkmcnt(6)
	v_mfma_f32_32x32x16_bf16 v[48:63], v[226:229], v[156:159], v[48:63]
	ds_read_b64_tr_b16 v[226:227], v185 offset:13312
	ds_read_b64_tr_b16 v[228:229], v185 offset:15360
	v_fmamk_f32 v81, v81, 0x3dd53b94, v251
	v_fmamk_f32 v82, v82, 0x3dd53b94, v251
	v_fmamk_f32 v83, v83, 0x3dd53b94, v251
	v_fmamk_f32 v84, v84, 0x3dd53b94, v251
	v_fmamk_f32 v85, v85, 0x3dd53b94, v251
	v_fmamk_f32 v86, v86, 0x3dd53b94, v251
	v_fmamk_f32 v87, v87, 0x3dd53b94, v251
	s_waitcnt lgkmcnt(6)
	v_mfma_f32_32x32x16_bf16 v[32:47], v[214:217], v[144:147], v[32:47]
	ds_read_b64_tr_b16 v[214:215], v185 offset:1536
	ds_read_b64_tr_b16 v[216:217], v185 offset:3584
	v_fmamk_f32 v88, v88, 0x3dd53b94, v251
	v_fmamk_f32 v89, v89, 0x3dd53b94, v251
	v_fmamk_f32 v90, v90, 0x3dd53b94, v251
	v_fmamk_f32 v91, v91, 0x3dd53b94, v251
	v_fmamk_f32 v92, v92, 0x3dd53b94, v251
	v_fmamk_f32 v93, v93, 0x3dd53b94, v251
	v_fmamk_f32 v94, v94, 0x3dd53b94, v251
	s_waitcnt lgkmcnt(6)
	v_mfma_f32_32x32x16_bf16 v[32:47], v[218:221], v[148:151], v[32:47]
	ds_read_b64_tr_b16 v[218:219], v185 offset:5632
	ds_read_b64_tr_b16 v[220:221], v185 offset:7680
	v_fmamk_f32 v95, v95, 0x3dd53b94, v251
	v_exp_f32_e32 v80, v80
	v_fmamk_f32 v64, v64, 0x3dd53b94, v251
	v_exp_f32_e32 v81, v81
	v_fmamk_f32 v65, v65, 0x3dd53b94, v251
	v_add_f32_e32 v212, 0, v80
	v_exp_f32_e32 v82, v82
	s_waitcnt lgkmcnt(6)
	v_mfma_f32_32x32x16_bf16 v[32:47], v[222:225], v[152:155], v[32:47]
	ds_read_b64_tr_b16 v[222:223], v185 offset:9728
	ds_read_b64_tr_b16 v[224:225], v185 offset:11776
	v_fmamk_f32 v66, v66, 0x3dd53b94, v251
	v_add_f32_e32 v212, v81, v212
	v_exp_f32_e32 v83, v83
	v_fmamk_f32 v67, v67, 0x3dd53b94, v251
	v_add_f32_e32 v212, v82, v212
	v_exp_f32_e32 v84, v84
	v_fmamk_f32 v68, v68, 0x3dd53b94, v251
	s_waitcnt lgkmcnt(6)
	v_mfma_f32_32x32x16_bf16 v[32:47], v[226:229], v[156:159], v[32:47]
	ds_read_b64_tr_b16 v[226:227], v185 offset:13824
	ds_read_b64_tr_b16 v[228:229], v185 offset:15872
	v_add_f32_e32 v212, v83, v212
	v_exp_f32_e32 v85, v85
	v_fmamk_f32 v69, v69, 0x3dd53b94, v251
	v_add_f32_e32 v212, v84, v212
	v_exp_f32_e32 v86, v86
	v_fmamk_f32 v70, v70, 0x3dd53b94, v251
	v_add_f32_e32 v212, v85, v212
	s_waitcnt lgkmcnt(6)
	v_mfma_f32_32x32x16_bf16 v[16:31], v[214:217], v[144:147], v[16:31]
	v_exp_f32_e32 v87, v87
	v_fmamk_f32 v71, v71, 0x3dd53b94, v251
	v_add_f32_e32 v212, v86, v212
	v_exp_f32_e32 v88, v88
	v_fmamk_f32 v72, v72, 0x3dd53b94, v251
	v_add_f32_e32 v212, v87, v212
	v_exp_f32_e32 v89, v89
	s_waitcnt lgkmcnt(4)
	v_mfma_f32_32x32x16_bf16 v[16:31], v[218:221], v[148:151], v[16:31]
	v_fmamk_f32 v73, v73, 0x3dd53b94, v251
	v_add_f32_e32 v212, v88, v212
	v_exp_f32_e32 v90, v90
	v_fmamk_f32 v74, v74, 0x3dd53b94, v251
	v_add_f32_e32 v212, v89, v212
	v_exp_f32_e32 v91, v91
	v_fmamk_f32 v75, v75, 0x3dd53b94, v251
	s_waitcnt lgkmcnt(2)
	v_mfma_f32_32x32x16_bf16 v[16:31], v[222:225], v[152:155], v[16:31]
	v_add_f32_e32 v212, v90, v212
	v_exp_f32_e32 v92, v92
	v_fmamk_f32 v76, v76, 0x3dd53b94, v251
	v_add_f32_e32 v212, v91, v212
	v_exp_f32_e32 v93, v93
	v_fmamk_f32 v77, v77, 0x3dd53b94, v251
	v_add_f32_e32 v212, v92, v212
	s_waitcnt lgkmcnt(0)
	v_mfma_f32_32x32x16_bf16 v[16:31], v[226:229], v[156:159], v[16:31]
	v_exp_f32_e32 v94, v94
	v_fmamk_f32 v78, v78, 0x3dd53b94, v251
	v_add_f32_e32 v212, v93, v212
	v_exp_f32_e32 v95, v95
	v_fmamk_f32 v79, v79, 0x3dd53b94, v251
	v_add_f32_e32 v212, v94, v212
	v_add_f32_e32 v212, v95, v212
	v_cvt_pk_bf16_f32 v144, v80, v81
	v_cvt_pk_bf16_f32 v145, v82, v83
	v_cvt_pk_bf16_f32 v146, v84, v85
	v_cvt_pk_bf16_f32 v147, v86, v87
	v_cvt_pk_bf16_f32 v148, v88, v89
	v_cvt_pk_bf16_f32 v149, v90, v91
	v_cvt_pk_bf16_f32 v150, v92, v93
	v_cvt_pk_bf16_f32 v151, v94, v95
	v_permlane32_swap_b32_e32 v144, v146
	v_permlane32_swap_b32_e32 v145, v147
	v_permlane32_swap_b32_e32 v148, v150
	v_permlane32_swap_b32_e32 v149, v151
	v_cmp_gt_f32_e32 vcc, 1.0, v207
	s_cbranch_vccz .Lmla_noresc_t
	v_mul_f32_e32 v0, v207, v0
	v_mul_f32_e32 v1, v207, v1
	v_mul_f32_e32 v2, v207, v2
	v_mul_f32_e32 v3, v207, v3
	v_mul_f32_e32 v4, v207, v4
	v_mul_f32_e32 v5, v207, v5
	v_mul_f32_e32 v6, v207, v6
	v_mul_f32_e32 v7, v207, v7
	v_mul_f32_e32 v8, v207, v8
	v_mul_f32_e32 v9, v207, v9
	v_mul_f32_e32 v10, v207, v10
	v_mul_f32_e32 v11, v207, v11
	v_mul_f32_e32 v12, v207, v12
	v_mul_f32_e32 v13, v207, v13
	v_mul_f32_e32 v14, v207, v14
	v_mul_f32_e32 v15, v207, v15
	v_mul_f32_e32 v48, v207, v48
	v_mul_f32_e32 v49, v207, v49
	v_mul_f32_e32 v50, v207, v50
	v_mul_f32_e32 v51, v207, v51
	v_mul_f32_e32 v52, v207, v52
	v_mul_f32_e32 v53, v207, v53
	v_mul_f32_e32 v54, v207, v54
	v_mul_f32_e32 v55, v207, v55
	v_mul_f32_e32 v56, v207, v56
	v_mul_f32_e32 v57, v207, v57
	v_mul_f32_e32 v58, v207, v58
	v_mul_f32_e32 v59, v207, v59
	v_mul_f32_e32 v60, v207, v60
	v_mul_f32_e32 v61, v207, v61
	v_mul_f32_e32 v62, v207, v62
	v_mul_f32_e32 v63, v207, v63
	v_mul_f32_e32 v32, v207, v32
	v_mul_f32_e32 v33, v207, v33
	v_mul_f32_e32 v34, v207, v34
	v_mul_f32_e32 v35, v207, v35
	v_mul_f32_e32 v36, v207, v36
	v_mul_f32_e32 v37, v207, v37
	v_mul_f32_e32 v38, v207, v38
	v_mul_f32_e32 v39, v207, v39
	v_mul_f32_e32 v40, v207, v40
	v_mul_f32_e32 v41, v207, v41
	v_mul_f32_e32 v42, v207, v42
	v_mul_f32_e32 v43, v207, v43
	v_mul_f32_e32 v44, v207, v44
	v_mul_f32_e32 v45, v207, v45
	v_mul_f32_e32 v46, v207, v46
	v_mul_f32_e32 v47, v207, v47
	v_mul_f32_e32 v16, v207, v16
	v_mul_f32_e32 v17, v207, v17
	v_mul_f32_e32 v18, v207, v18
	v_mul_f32_e32 v19, v207, v19
	v_mul_f32_e32 v20, v207, v20
	v_mul_f32_e32 v21, v207, v21
	v_mul_f32_e32 v22, v207, v22
	v_mul_f32_e32 v23, v207, v23
	v_mul_f32_e32 v24, v207, v24
	v_mul_f32_e32 v25, v207, v25
	v_mul_f32_e32 v26, v207, v26
	v_mul_f32_e32 v27, v207, v27
	v_mul_f32_e32 v28, v207, v28
	v_mul_f32_e32 v29, v207, v29
	v_mul_f32_e32 v30, v207, v30
	v_mul_f32_e32 v31, v207, v31
.Lmla_noresc_t:
	s_waitcnt vmcnt(0) lgkmcnt(0)
	s_barrier
	ds_read_b64_tr_b16 v[214:215], v184
	ds_read_b64_tr_b16 v[216:217], v184 offset:2048
	ds_read_b64_tr_b16 v[218:219], v184 offset:4096
	ds_read_b64_tr_b16 v[220:221], v184 offset:6144
	ds_read_b64_tr_b16 v[222:223], v184 offset:8192
	ds_read_b64_tr_b16 v[224:225], v184 offset:10240
	ds_read_b64_tr_b16 v[226:227], v184 offset:12288
	ds_read_b64_tr_b16 v[228:229], v184 offset:14336
	v_exp_f32_e32 v64, v64
	v_exp_f32_e32 v65, v65
	v_add_f32_e32 v212, v64, v212
	v_exp_f32_e32 v66, v66
	v_add_f32_e32 v212, v65, v212
	v_exp_f32_e32 v67, v67
	v_add_f32_e32 v212, v66, v212
	v_exp_f32_e32 v68, v68
	v_add_f32_e32 v212, v67, v212
	v_exp_f32_e32 v69, v69
	v_add_f32_e32 v212, v68, v212
	v_exp_f32_e32 v70, v70
	v_add_f32_e32 v212, v69, v212
	v_exp_f32_e32 v71, v71
	v_add_f32_e32 v212, v70, v212
	v_exp_f32_e32 v72, v72
	v_add_f32_e32 v212, v71, v212
	v_exp_f32_e32 v73, v73
	v_add_f32_e32 v212, v72, v212
	v_exp_f32_e32 v74, v74
	v_add_f32_e32 v212, v73, v212
	v_exp_f32_e32 v75, v75
	v_add_f32_e32 v212, v74, v212
	v_exp_f32_e32 v76, v76
	v_add_f32_e32 v212, v75, v212
	v_exp_f32_e32 v77, v77
	v_add_f32_e32 v212, v76, v212
	v_exp_f32_e32 v78, v78
	v_add_f32_e32 v212, v77, v212
	v_exp_f32_e32 v79, v79
	v_add_f32_e32 v212, v78, v212
	v_add_f32_e32 v212, v79, v212
	v_mov_b32_e32 v213, v212
	v_cvt_pk_bf16_f32 v152, v64, v65
	v_cvt_pk_bf16_f32 v153, v66, v67
	v_cvt_pk_bf16_f32 v154, v68, v69
	v_cvt_pk_bf16_f32 v155, v70, v71
	v_cvt_pk_bf16_f32 v156, v72, v73
	v_cvt_pk_bf16_f32 v157, v74, v75
	v_cvt_pk_bf16_f32 v158, v76, v77
	v_cvt_pk_bf16_f32 v159, v78, v79
	v_permlane32_swap_b32_e32 v212, v213
	v_add_f32_e32 v252, v212, v213
	v_fma_f32 v183, v207, v183, v252
	v_permlane32_swap_b32_e32 v152, v154
	v_permlane32_swap_b32_e32 v153, v155
	v_permlane32_swap_b32_e32 v156, v158
	v_permlane32_swap_b32_e32 v157, v159
	s_waitcnt lgkmcnt(6)
	v_mfma_f32_32x32x16_bf16 v[0:15], v[214:217], v[144:147], v[0:15]
	ds_read_b64_tr_b16 v[214:215], v184 offset:512
	ds_read_b64_tr_b16 v[216:217], v184 offset:2560
	s_waitcnt lgkmcnt(6)
	v_mfma_f32_32x32x16_bf16 v[0:15], v[218:221], v[148:151], v[0:15]
	ds_read_b64_tr_b16 v[218:219], v184 offset:4608
	ds_read_b64_tr_b16 v[220:221], v184 offset:6656
	s_waitcnt lgkmcnt(6)
	v_mfma_f32_32x32x16_bf16 v[0:15], v[222:225], v[152:155], v[0:15]
	ds_read_b64_tr_b16 v[222:223], v184 offset:8704
	ds_read_b64_tr_b16 v[224:225], v184 offset:10752
	s_waitcnt lgkmcnt(6)
	v_mfma_f32_32x32x16_bf16 v[0:15], v[226:229], v[156:159], v[0:15]
	ds_read_b64_tr_b16 v[226:227], v184 offset:12800
	ds_read_b64_tr_b16 v[228:229], v184 offset:14848
	s_waitcnt lgkmcnt(6)
	v_mfma_f32_32x32x16_bf16 v[48:63], v[214:217], v[144:147], v[48:63]
	ds_read_b64_tr_b16 v[214:215], v184 offset:1024
	ds_read_b64_tr_b16 v[216:217], v184 offset:3072
	s_waitcnt lgkmcnt(6)
	v_mfma_f32_32x32x16_bf16 v[48:63], v[218:221], v[148:151], v[48:63]
	ds_read_b64_tr_b16 v[218:219], v184 offset:5120
	ds_read_b64_tr_b16 v[220:221], v184 offset:7168
	s_waitcnt lgkmcnt(6)
	v_mfma_f32_32x32x16_bf16 v[48:63], v[222:225], v[152:155], v[48:63]
	ds_read_b64_tr_b16 v[222:223], v184 offset:9216
	ds_read_b64_tr_b16 v[224:225], v184 offset:11264
	s_waitcnt lgkmcnt(6)
	v_mfma_f32_32x32x16_bf16 v[48:63], v[226:229], v[156:159], v[48:63]
	ds_read_b64_tr_b16 v[226:227], v184 offset:13312
	ds_read_b64_tr_b16 v[228:229], v184 offset:15360
	s_waitcnt lgkmcnt(6)
	v_mfma_f32_32x32x16_bf16 v[32:47], v[214:217], v[144:147], v[32:47]
	ds_read_b64_tr_b16 v[214:215], v184 offset:1536
	ds_read_b64_tr_b16 v[216:217], v184 offset:3584
	s_waitcnt lgkmcnt(6)
	v_mfma_f32_32x32x16_bf16 v[32:47], v[218:221], v[148:151], v[32:47]
	ds_read_b64_tr_b16 v[218:219], v184 offset:5632
	ds_read_b64_tr_b16 v[220:221], v184 offset:7680
	s_waitcnt lgkmcnt(6)
	v_mfma_f32_32x32x16_bf16 v[32:47], v[222:225], v[152:155], v[32:47]
	ds_read_b64_tr_b16 v[222:223], v184 offset:9728
	ds_read_b64_tr_b16 v[224:225], v184 offset:11776
	s_waitcnt lgkmcnt(6)
	v_mfma_f32_32x32x16_bf16 v[32:47], v[226:229], v[156:159], v[32:47]
	ds_read_b64_tr_b16 v[226:227], v184 offset:13824
	ds_read_b64_tr_b16 v[228:229], v184 offset:15872
	s_waitcnt lgkmcnt(6)
	v_mfma_f32_32x32x16_bf16 v[16:31], v[214:217], v[144:147], v[16:31]
	s_waitcnt lgkmcnt(4)
	v_mfma_f32_32x32x16_bf16 v[16:31], v[218:221], v[148:151], v[16:31]
	s_waitcnt lgkmcnt(2)
	v_mfma_f32_32x32x16_bf16 v[16:31], v[222:225], v[152:155], v[16:31]
	s_waitcnt lgkmcnt(0)
	v_mfma_f32_32x32x16_bf16 v[16:31], v[226:229], v[156:159], v[16:31]
	s_setprio 0
	s_ashr_i32 s13, s12, 31
	s_lshl_b64 s[0:1], s[12:13], 12
	s_add_u32 s0, s4, s0
	s_addc_u32 s1, s5, s1
	v_rcp_f32_e32 v213, v183
	v_lshlrev_b32_e32 v160, 12, v170
	v_lshl_add_u32 v160, v171, 4, v160
	s_nop 1
	v_lshl_add_u64 v[254:255], s[0:1], 0, v[160:161]
	v_mul_f32_e32 v0, v213, v0
	v_mul_f32_e32 v1, v213, v1
	v_mul_f32_e32 v2, v213, v2
	v_mul_f32_e32 v3, v213, v3
	v_mul_f32_e32 v4, v213, v4
	v_mul_f32_e32 v5, v213, v5
	v_mul_f32_e32 v6, v213, v6
	v_mul_f32_e32 v7, v213, v7
	v_mul_f32_e32 v8, v213, v8
	v_mul_f32_e32 v9, v213, v9
	v_mul_f32_e32 v10, v213, v10
	v_mul_f32_e32 v11, v213, v11
	v_mul_f32_e32 v12, v213, v12
	v_mul_f32_e32 v13, v213, v13
	v_mul_f32_e32 v14, v213, v14
	v_mul_f32_e32 v15, v213, v15
	v_cvt_pk_bf16_f32 v0, v0, v1
	v_cvt_pk_bf16_f32 v1, v2, v3
	v_cvt_pk_bf16_f32 v2, v4, v5
	v_cvt_pk_bf16_f32 v3, v6, v7
	v_cvt_pk_bf16_f32 v4, v8, v9
	v_cvt_pk_bf16_f32 v5, v10, v11
	v_cvt_pk_bf16_f32 v6, v12, v13
	v_cvt_pk_bf16_f32 v7, v14, v15
	s_nop 1
	v_permlane32_swap_b32_e32 v0, v2
	v_permlane32_swap_b32_e32 v1, v3
	v_permlane32_swap_b32_e32 v4, v6
	v_permlane32_swap_b32_e32 v5, v7
	global_store_dwordx4 v[254:255], v[0:3], off
	global_store_dwordx4 v[254:255], v[4:7], off offset:32
	v_mul_f32_e32 v48, v213, v48
	v_mul_f32_e32 v49, v213, v49
	v_mul_f32_e32 v50, v213, v50
	v_mul_f32_e32 v51, v213, v51
	v_mul_f32_e32 v52, v213, v52
	v_mul_f32_e32 v53, v213, v53
	v_mul_f32_e32 v54, v213, v54
	v_mul_f32_e32 v55, v213, v55
	v_mul_f32_e32 v56, v213, v56
	v_mul_f32_e32 v57, v213, v57
	v_mul_f32_e32 v58, v213, v58
	v_mul_f32_e32 v59, v213, v59
	v_mul_f32_e32 v60, v213, v60
	v_mul_f32_e32 v61, v213, v61
	v_mul_f32_e32 v62, v213, v62
	v_mul_f32_e32 v63, v213, v63
	v_cvt_pk_bf16_f32 v48, v48, v49
	v_cvt_pk_bf16_f32 v49, v50, v51
	v_cvt_pk_bf16_f32 v50, v52, v53
	v_cvt_pk_bf16_f32 v51, v54, v55
	v_cvt_pk_bf16_f32 v52, v56, v57
	v_cvt_pk_bf16_f32 v53, v58, v59
	v_cvt_pk_bf16_f32 v54, v60, v61
	v_cvt_pk_bf16_f32 v55, v62, v63
	s_nop 1
	v_permlane32_swap_b32_e32 v48, v50
	v_permlane32_swap_b32_e32 v49, v51
	v_permlane32_swap_b32_e32 v52, v54
	v_permlane32_swap_b32_e32 v53, v55
	global_store_dwordx4 v[254:255], v[48:51], off offset:64
	global_store_dwordx4 v[254:255], v[52:55], off offset:96
	v_mul_f32_e32 v32, v213, v32
	v_mul_f32_e32 v33, v213, v33
	v_mul_f32_e32 v34, v213, v34
	v_mul_f32_e32 v35, v213, v35
	v_mul_f32_e32 v36, v213, v36
	v_mul_f32_e32 v37, v213, v37
	v_mul_f32_e32 v38, v213, v38
	v_mul_f32_e32 v39, v213, v39
	v_mul_f32_e32 v40, v213, v40
	v_mul_f32_e32 v41, v213, v41
	v_mul_f32_e32 v42, v213, v42
	v_mul_f32_e32 v43, v213, v43
	v_mul_f32_e32 v44, v213, v44
	v_mul_f32_e32 v45, v213, v45
	v_mul_f32_e32 v46, v213, v46
	v_mul_f32_e32 v47, v213, v47
	v_cvt_pk_bf16_f32 v32, v32, v33
	v_cvt_pk_bf16_f32 v33, v34, v35
	v_cvt_pk_bf16_f32 v34, v36, v37
	v_cvt_pk_bf16_f32 v35, v38, v39
	v_cvt_pk_bf16_f32 v36, v40, v41
	v_cvt_pk_bf16_f32 v37, v42, v43
	v_cvt_pk_bf16_f32 v38, v44, v45
	v_cvt_pk_bf16_f32 v39, v46, v47
	s_nop 1
	v_permlane32_swap_b32_e32 v32, v34
	v_permlane32_swap_b32_e32 v33, v35
	v_permlane32_swap_b32_e32 v36, v38
	v_permlane32_swap_b32_e32 v37, v39
	global_store_dwordx4 v[254:255], v[32:35], off offset:128
	global_store_dwordx4 v[254:255], v[36:39], off offset:160
	v_mul_f32_e32 v16, v213, v16
	v_mul_f32_e32 v17, v213, v17
	v_mul_f32_e32 v18, v213, v18
	v_mul_f32_e32 v19, v213, v19
	v_mul_f32_e32 v20, v213, v20
	v_mul_f32_e32 v21, v213, v21
	v_mul_f32_e32 v22, v213, v22
	v_mul_f32_e32 v23, v213, v23
	v_mul_f32_e32 v24, v213, v24
	v_mul_f32_e32 v25, v213, v25
	v_mul_f32_e32 v26, v213, v26
	v_mul_f32_e32 v27, v213, v27
	v_mul_f32_e32 v28, v213, v28
	v_mul_f32_e32 v29, v213, v29
	v_mul_f32_e32 v30, v213, v30
	v_mul_f32_e32 v31, v213, v31
	v_cvt_pk_bf16_f32 v16, v16, v17
	v_cvt_pk_bf16_f32 v17, v18, v19
	v_cvt_pk_bf16_f32 v18, v20, v21
	v_cvt_pk_bf16_f32 v19, v22, v23
	v_cvt_pk_bf16_f32 v20, v24, v25
	v_cvt_pk_bf16_f32 v21, v26, v27
	v_cvt_pk_bf16_f32 v22, v28, v29
	v_cvt_pk_bf16_f32 v23, v30, v31
	s_nop 1
	v_permlane32_swap_b32_e32 v16, v18
	v_permlane32_swap_b32_e32 v17, v19
	v_permlane32_swap_b32_e32 v20, v22
	v_permlane32_swap_b32_e32 v21, v23
	global_store_dwordx4 v[254:255], v[16:19], off offset:192
	global_store_dwordx4 v[254:255], v[20:23], off offset:224
	s_waitcnt lgkmcnt(0)
	s_barrier
	s_add_i32 s15, s15, s34
	s_cmp_lt_i32 s15, s14
	s_cbranch_scc0 .LBB0_729
	s_branch .LBB0_551
